# compress epilogue (partial-sum exchange, gelu, stage 2, store) at wave priority 2 over the other workgroup's weight stream
# speedup vs baseline: 1.0020x; 1.0020x over previous
; __device__ __forceinline__ u32x2 pack4(f32x4 v) { u32x2 r; r.x = cvt_pk_bf16(v[0], v[1]); r.y = cvt_pk_bf16(v[2], v[3]); return r; }
; __device__ __forceinline__ void compress_task(const Params& p, int task, char* smem) {
;     ...
;         *(u32x2*)(kc + ((size_t)bg * 256 + n) * 64 + w * 16 + fq * 4) = pack4(o);
;     } else {
;         bf16_t* vct = (bf16_t*)(p.ws + OFF_VCT);
; #pragma unroll
;         for (int j = 0; j < 4; ++j) if (n0 + fq * 4 + j >= 255) o[j] = 0.f;
;         *(u32x2*)(vct + (((size_t)bg * 16 + (n0 >> 4)) * 64 + w * 16 + fr) * 16 + fq * 4) = pack4(o);
;     }
;     __syncthreads();
; __global__ void __launch_bounds__(256, 2) fwd_megakernel(Params p) {
;     ...
;     for (int task = blockIdx.x; task < 1024; task += G) compress_task(p, task, smem);
.LBB0_248:
	s_setprio 0
	v_lshl_add_u64 v[0:1], v[64:65], 1, v[6:7]
	v_mov_b32_e32 v89, v65
	s_add_i32 s42, s42, s58
	s_add_i32 s20, s20, s21
	v_lshl_add_u64 v[0:1], v[0:1], 0, v[88:89]
	s_cmpk_gt_i32 s42, 0x3ff
	global_store_dwordx2 v[0:1], v[4:5], off
	s_waitcnt lgkmcnt(0)
	s_barrier
	s_cbranch_scc1 .LBB0_292

; __device__ __forceinline__ u32x2 pack4(f32x4 v) { u32x2 r; r.x = cvt_pk_bf16(v[0], v[1]); r.y = cvt_pk_bf16(v[2], v[3]); return r; }
; __device__ __forceinline__ void compress_task(const Params& p, int task, char* smem) {
;     ...
;     __syncthreads();
;     if (w == 0) {
; #pragma unroll
;         for (int nt = 0; nt < 16; ++nt) {
;             f32x4 v = acc[nt];
; #pragma unroll
;             for (int ww = 0; ww < 3; ++ww) v = v + *(const f32x4*)(red + (ww * 16 + fr) * 260 + nt * 16 + fq * 4);
; #pragma unroll
;             for (int j = 0; j < 4; ++j) v[j] = gelu_tanh(v[j]);
;             *(u32x2*)(hid + fr * 264 + nt * 16 + fq * 4) = pack4(v);
;         }
.LBB0_253:
	s_setprio 2
	s_or_b64 exec, exec, s[18:19]
	s_waitcnt lgkmcnt(0)
	s_barrier
	s_and_saveexec_b64 s[18:19], s[4:5]
	s_cbranch_execz .LBB0_255
	ds_read_b128 v[90:93], v100
	ds_read_b128 v[94:97], v100 offset:16640
	ds_read_b128 v[106:109], v100 offset:33280
	s_waitcnt lgkmcnt(2)
	v_pk_add_f32 v[60:61], v[60:61], v[90:91]
	s_waitcnt lgkmcnt(1)
	v_pk_add_f32 v[60:61], v[60:61], v[94:95]
	v_pk_add_f32 v[62:63], v[62:63], v[92:93]
	s_waitcnt lgkmcnt(0)
	v_pk_add_f32 v[60:61], v[60:61], v[106:107]
	v_pk_add_f32 v[62:63], v[62:63], v[96:97]
	v_mul_f32_e32 v64, 0x3d372713, v60
	v_mul_f32_e32 v64, v60, v64
	v_mul_f32_e32 v89, 0x3d372713, v61
	v_fma_f32 v64, v60, v64, v60
	v_mul_f32_e32 v89, v61, v89
	v_mul_f32_e32 v64, 0x3f4c422a, v64
	v_fma_f32 v89, v61, v89, v61
	v_add_f32_e32 v64, v64, v64
	v_mul_f32_e32 v89, 0x3f4c422a, v89
	v_mul_f32_e32 v64, 0x3fb8aa3b, v64
	v_add_f32_e32 v89, v89, v89
	v_exp_f32_e32 v64, v64
	v_mul_f32_e32 v89, 0x3fb8aa3b, v89
	v_exp_f32_e32 v89, v89
	v_pk_add_f32 v[62:63], v[62:63], v[108:109]
	v_add_f32_e32 v64, 1.0, v64
	v_rcp_f32_e32 v90, v64
	v_add_f32_e32 v64, 1.0, v89
	v_rcp_f32_e32 v91, v64
	v_mul_f32_e32 v64, 0x3d372713, v62
	v_mul_f32_e32 v64, v62, v64
	v_mul_f32_e32 v89, 0x3d372713, v63
	v_fma_f32 v64, v62, v64, v62
	v_mul_f32_e32 v89, v63, v89
	v_mul_f32_e32 v64, 0x3f4c422a, v64
	v_fma_f32 v89, v63, v89, v63
	v_add_f32_e32 v64, v64, v64
	v_mul_f32_e32 v89, 0x3f4c422a, v89
	v_mul_f32_e32 v64, 0x3fb8aa3b, v64
	v_add_f32_e32 v89, v89, v89
	v_exp_f32_e32 v64, v64
	v_mul_f32_e32 v89, 0x3fb8aa3b, v89
	v_exp_f32_e32 v89, v89
	v_pk_fma_f32 v[90:91], v[90:91], 2.0, 1.0 op_sel_hi:[1,0,0] neg_lo:[1,0,0] neg_hi:[1,0,0]
	v_add_f32_e32 v64, 1.0, v64
	v_rcp_f32_e32 v92, v64
	v_add_f32_e32 v64, 1.0, v89
	v_rcp_f32_e32 v93, v64
	v_pk_mul_f32 v[60:61], v[60:61], 0.5 op_sel_hi:[1,0]
	v_pk_add_f32 v[90:91], v[90:91], 1.0 op_sel_hi:[1,0]
	v_pk_mul_f32 v[62:63], v[62:63], 0.5 op_sel_hi:[1,0]
	v_pk_mul_f32 v[60:61], v[60:61], v[90:91]
	v_pk_fma_f32 v[90:91], v[92:93], 2.0, 1.0 op_sel_hi:[1,0,0] neg_lo:[1,0,0] neg_hi:[1,0,0]
	v_cvt_pk_bf16_f32 v60, v60, v61
	v_pk_add_f32 v[90:91], v[90:91], 1.0 op_sel_hi:[1,0]
	s_nop 0
	v_pk_mul_f32 v[62:63], v[62:63], v[90:91]
	s_nop 0
	v_cvt_pk_bf16_f32 v61, v62, v63
	ds_write_b64 v101, v[60:61] offset:49920
	ds_read_b128 v[60:63], v100 offset:64
	ds_read_b128 v[90:93], v100 offset:16704
	ds_read_b128 v[94:97], v100 offset:33344
	s_waitcnt lgkmcnt(2)
	v_pk_add_f32 v[56:57], v[56:57], v[60:61]
	s_waitcnt lgkmcnt(1)
	v_pk_add_f32 v[56:57], v[56:57], v[90:91]
	v_pk_add_f32 v[58:59], v[58:59], v[62:63]
	s_waitcnt lgkmcnt(0)
	v_pk_add_f32 v[56:57], v[56:57], v[94:95]
	v_pk_add_f32 v[58:59], v[58:59], v[92:93]
	v_mul_f32_e32 v60, 0x3d372713, v56
	v_mul_f32_e32 v61, 0x3d372713, v57
	v_mul_f32_e32 v60, v56, v60
	v_mul_f32_e32 v61, v57, v61
	v_pk_add_f32 v[58:59], v[58:59], v[96:97]
	v_fma_f32 v60, v56, v60, v56
	v_fma_f32 v61, v57, v61, v57
	v_mul_f32_e32 v62, 0x3d372713, v58
	v_mul_f32_e32 v63, 0x3d372713, v59
	v_mul_f32_e32 v60, 0x3f4c422a, v60
	v_mul_f32_e32 v61, 0x3f4c422a, v61
	v_mul_f32_e32 v62, v58, v62
	v_mul_f32_e32 v63, v59, v63
	v_add_f32_e32 v60, v60, v60
	v_add_f32_e32 v61, v61, v61
	v_fma_f32 v62, v58, v62, v58
	v_fma_f32 v63, v59, v63, v59
	v_mul_f32_e32 v60, 0x3fb8aa3b, v60
	v_mul_f32_e32 v61, 0x3fb8aa3b, v61
	v_mul_f32_e32 v62, 0x3f4c422a, v62
	v_mul_f32_e32 v63, 0x3f4c422a, v63
	v_exp_f32_e32 v60, v60
	v_exp_f32_e32 v61, v61
	v_add_f32_e32 v62, v62, v62
	v_add_f32_e32 v63, v63, v63
	v_mul_f32_e32 v62, 0x3fb8aa3b, v62
	v_mul_f32_e32 v63, 0x3fb8aa3b, v63
	v_exp_f32_e32 v62, v62
	v_exp_f32_e32 v63, v63
	v_add_f32_e32 v60, 1.0, v60
	v_add_f32_e32 v61, 1.0, v61
	v_rcp_f32_e32 v60, v60
	v_rcp_f32_e32 v61, v61
	v_add_f32_e32 v62, 1.0, v62
	v_add_f32_e32 v63, 1.0, v63
	v_rcp_f32_e32 v62, v62
	v_rcp_f32_e32 v63, v63
	v_pk_fma_f32 v[60:61], v[60:61], 2.0, 1.0 op_sel_hi:[1,0,0] neg_lo:[1,0,0] neg_hi:[1,0,0]
	v_pk_mul_f32 v[56:57], v[56:57], 0.5 op_sel_hi:[1,0]
	v_pk_add_f32 v[60:61], v[60:61], 1.0 op_sel_hi:[1,0]
	v_pk_mul_f32 v[58:59], v[58:59], 0.5 op_sel_hi:[1,0]
	v_pk_mul_f32 v[56:57], v[56:57], v[60:61]
	v_pk_fma_f32 v[60:61], v[62:63], 2.0, 1.0 op_sel_hi:[1,0,0] neg_lo:[1,0,0] neg_hi:[1,0,0]
	v_cvt_pk_bf16_f32 v56, v56, v57
	v_pk_add_f32 v[60:61], v[60:61], 1.0 op_sel_hi:[1,0]
	s_nop 0
	v_pk_mul_f32 v[58:59], v[58:59], v[60:61]
	s_nop 0
	v_cvt_pk_bf16_f32 v57, v58, v59
	ds_write_b64 v101, v[56:57] offset:49952
	ds_read_b128 v[56:59], v100 offset:128
	ds_read_b128 v[60:63], v100 offset:16768
	ds_read_b128 v[90:93], v100 offset:33408
	s_waitcnt lgkmcnt(2)
	v_pk_add_f32 v[52:53], v[52:53], v[56:57]
	s_waitcnt lgkmcnt(1)
	v_pk_add_f32 v[52:53], v[52:53], v[60:61]
	v_pk_add_f32 v[54:55], v[54:55], v[58:59]
	s_waitcnt lgkmcnt(0)
; __device__ __forceinline__ u32x2 pack4(f32x4 v) { u32x2 r; r.x = cvt_pk_bf16(v[0], v[1]); r.y = cvt_pk_bf16(v[2], v[3]); return r; }
; __device__ __forceinline__ void compress_task(const Params& p, int task, char* smem) {
;     ...
; #pragma unroll
;         for (int nt = 0; nt < 16; ++nt) {
;             f32x4 v = acc[nt];
; #pragma unroll
;             for (int ww = 0; ww < 3; ++ww) v = v + *(const f32x4*)(red + (ww * 16 + fr) * 260 + nt * 16 + fq * 4);
; #pragma unroll
;             for (int j = 0; j < 4; ++j) v[j] = gelu_tanh(v[j]);
;             *(u32x2*)(hid + fr * 264 + nt * 16 + fq * 4) = pack4(v);
;         }
	v_pk_add_f32 v[52:53], v[52:53], v[90:91]
	v_pk_add_f32 v[54:55], v[54:55], v[62:63]
	v_mul_f32_e32 v56, 0x3d372713, v52
	v_mul_f32_e32 v57, 0x3d372713, v53
	v_mul_f32_e32 v56, v52, v56
	v_mul_f32_e32 v57, v53, v57
	v_pk_add_f32 v[54:55], v[54:55], v[92:93]
	v_fma_f32 v56, v52, v56, v52
	v_fma_f32 v57, v53, v57, v53
	v_mul_f32_e32 v58, 0x3d372713, v54
	v_mul_f32_e32 v59, 0x3d372713, v55
	v_mul_f32_e32 v56, 0x3f4c422a, v56
	v_mul_f32_e32 v57, 0x3f4c422a, v57
	v_mul_f32_e32 v58, v54, v58
	v_mul_f32_e32 v59, v55, v59
	v_add_f32_e32 v56, v56, v56
	v_add_f32_e32 v57, v57, v57
	v_fma_f32 v58, v54, v58, v54
	v_fma_f32 v59, v55, v59, v55
	v_mul_f32_e32 v56, 0x3fb8aa3b, v56
	v_mul_f32_e32 v57, 0x3fb8aa3b, v57
	v_mul_f32_e32 v58, 0x3f4c422a, v58
	v_mul_f32_e32 v59, 0x3f4c422a, v59
	v_exp_f32_e32 v56, v56
	v_exp_f32_e32 v57, v57
	v_add_f32_e32 v58, v58, v58
	v_add_f32_e32 v59, v59, v59
	v_mul_f32_e32 v58, 0x3fb8aa3b, v58
	v_mul_f32_e32 v59, 0x3fb8aa3b, v59
	v_exp_f32_e32 v58, v58
	v_exp_f32_e32 v59, v59
	v_add_f32_e32 v56, 1.0, v56
	v_add_f32_e32 v57, 1.0, v57
	v_rcp_f32_e32 v56, v56
	v_rcp_f32_e32 v57, v57
	v_add_f32_e32 v58, 1.0, v58
	v_add_f32_e32 v59, 1.0, v59
	v_rcp_f32_e32 v58, v58
	v_rcp_f32_e32 v59, v59
	v_pk_fma_f32 v[56:57], v[56:57], 2.0, 1.0 op_sel_hi:[1,0,0] neg_lo:[1,0,0] neg_hi:[1,0,0]
	v_pk_mul_f32 v[52:53], v[52:53], 0.5 op_sel_hi:[1,0]
	v_pk_add_f32 v[56:57], v[56:57], 1.0 op_sel_hi:[1,0]
	v_pk_mul_f32 v[54:55], v[54:55], 0.5 op_sel_hi:[1,0]
	v_pk_mul_f32 v[52:53], v[52:53], v[56:57]
	v_pk_fma_f32 v[56:57], v[58:59], 2.0, 1.0 op_sel_hi:[1,0,0] neg_lo:[1,0,0] neg_hi:[1,0,0]
	v_cvt_pk_bf16_f32 v52, v52, v53
	v_pk_add_f32 v[56:57], v[56:57], 1.0 op_sel_hi:[1,0]
	s_nop 0
	v_pk_mul_f32 v[54:55], v[54:55], v[56:57]
	s_nop 0
	v_cvt_pk_bf16_f32 v53, v54, v55
	ds_write_b64 v101, v[52:53] offset:49984
	ds_read_b128 v[52:55], v100 offset:192
	ds_read_b128 v[56:59], v100 offset:16832
	ds_read_b128 v[60:63], v100 offset:33472
	s_waitcnt lgkmcnt(2)
	v_pk_add_f32 v[48:49], v[48:49], v[52:53]
	s_waitcnt lgkmcnt(1)
	v_pk_add_f32 v[48:49], v[48:49], v[56:57]
	v_pk_add_f32 v[50:51], v[50:51], v[54:55]
	s_waitcnt lgkmcnt(0)
	v_pk_add_f32 v[48:49], v[48:49], v[60:61]
	v_pk_add_f32 v[50:51], v[50:51], v[58:59]
	v_mul_f32_e32 v52, 0x3d372713, v48
	v_mul_f32_e32 v53, 0x3d372713, v49
	v_mul_f32_e32 v52, v48, v52
	v_mul_f32_e32 v53, v49, v53
	v_pk_add_f32 v[50:51], v[50:51], v[62:63]
	v_fma_f32 v52, v48, v52, v48
	v_fma_f32 v53, v49, v53, v49
	v_mul_f32_e32 v54, 0x3d372713, v50
	v_mul_f32_e32 v55, 0x3d372713, v51
	v_mul_f32_e32 v52, 0x3f4c422a, v52
	v_mul_f32_e32 v53, 0x3f4c422a, v53
	v_mul_f32_e32 v54, v50, v54
	v_mul_f32_e32 v55, v51, v55
	v_add_f32_e32 v52, v52, v52
	v_add_f32_e32 v53, v53, v53
	v_fma_f32 v54, v50, v54, v50
	v_fma_f32 v55, v51, v55, v51
	v_mul_f32_e32 v52, 0x3fb8aa3b, v52
	v_mul_f32_e32 v53, 0x3fb8aa3b, v53
	v_mul_f32_e32 v54, 0x3f4c422a, v54
	v_mul_f32_e32 v55, 0x3f4c422a, v55
	v_exp_f32_e32 v52, v52
	v_exp_f32_e32 v53, v53
	v_add_f32_e32 v54, v54, v54
	v_add_f32_e32 v55, v55, v55
	v_mul_f32_e32 v54, 0x3fb8aa3b, v54
	v_mul_f32_e32 v55, 0x3fb8aa3b, v55
	v_exp_f32_e32 v54, v54
	v_exp_f32_e32 v55, v55
	v_add_f32_e32 v52, 1.0, v52
	v_add_f32_e32 v53, 1.0, v53
	v_rcp_f32_e32 v52, v52
	v_rcp_f32_e32 v53, v53
	v_add_f32_e32 v54, 1.0, v54
	v_add_f32_e32 v55, 1.0, v55
	v_rcp_f32_e32 v54, v54
	v_rcp_f32_e32 v55, v55
	v_pk_fma_f32 v[52:53], v[52:53], 2.0, 1.0 op_sel_hi:[1,0,0] neg_lo:[1,0,0] neg_hi:[1,0,0]
	v_pk_mul_f32 v[48:49], v[48:49], 0.5 op_sel_hi:[1,0]
	v_pk_add_f32 v[52:53], v[52:53], 1.0 op_sel_hi:[1,0]
	v_pk_mul_f32 v[50:51], v[50:51], 0.5 op_sel_hi:[1,0]
	v_pk_mul_f32 v[48:49], v[48:49], v[52:53]
	v_pk_fma_f32 v[52:53], v[54:55], 2.0, 1.0 op_sel_hi:[1,0,0] neg_lo:[1,0,0] neg_hi:[1,0,0]
	v_cvt_pk_bf16_f32 v48, v48, v49
	v_pk_add_f32 v[52:53], v[52:53], 1.0 op_sel_hi:[1,0]
	s_nop 0
	v_pk_mul_f32 v[50:51], v[50:51], v[52:53]
	s_nop 0
	v_cvt_pk_bf16_f32 v49, v50, v51
	ds_write_b64 v101, v[48:49] offset:50016
	ds_read_b128 v[48:51], v100 offset:256
	ds_read_b128 v[52:55], v100 offset:16896
	ds_read_b128 v[56:59], v100 offset:33536
	s_waitcnt lgkmcnt(2)
	v_pk_add_f32 v[44:45], v[44:45], v[48:49]
	s_waitcnt lgkmcnt(1)
	v_pk_add_f32 v[44:45], v[44:45], v[52:53]
	v_pk_add_f32 v[46:47], v[46:47], v[50:51]
	s_waitcnt lgkmcnt(0)
	v_pk_add_f32 v[44:45], v[44:45], v[56:57]
	v_pk_add_f32 v[46:47], v[46:47], v[54:55]
	v_mul_f32_e32 v48, 0x3d372713, v44
	v_mul_f32_e32 v49, 0x3d372713, v45
	v_mul_f32_e32 v48, v44, v48
	v_mul_f32_e32 v49, v45, v49
	v_pk_add_f32 v[46:47], v[46:47], v[58:59]
	v_fma_f32 v48, v44, v48, v44
	v_fma_f32 v49, v45, v49, v45
	v_mul_f32_e32 v50, 0x3d372713, v46
	v_mul_f32_e32 v51, 0x3d372713, v47
	v_mul_f32_e32 v48, 0x3f4c422a, v48
	v_mul_f32_e32 v49, 0x3f4c422a, v49
	v_mul_f32_e32 v50, v46, v50
	v_mul_f32_e32 v51, v47, v51
	v_add_f32_e32 v48, v48, v48
	v_add_f32_e32 v49, v49, v49
	v_fma_f32 v50, v46, v50, v46
	v_fma_f32 v51, v47, v51, v47
	v_mul_f32_e32 v48, 0x3fb8aa3b, v48
	v_mul_f32_e32 v49, 0x3fb8aa3b, v49
	v_mul_f32_e32 v50, 0x3f4c422a, v50
	v_mul_f32_e32 v51, 0x3f4c422a, v51
	v_exp_f32_e32 v48, v48
	v_exp_f32_e32 v49, v49
	v_add_f32_e32 v50, v50, v50
	v_add_f32_e32 v51, v51, v51
	v_mul_f32_e32 v50, 0x3fb8aa3b, v50
	v_mul_f32_e32 v51, 0x3fb8aa3b, v51
	v_exp_f32_e32 v50, v50
	v_exp_f32_e32 v51, v51
	v_add_f32_e32 v48, 1.0, v48
	v_add_f32_e32 v49, 1.0, v49
	v_rcp_f32_e32 v48, v48
	v_rcp_f32_e32 v49, v49
	v_add_f32_e32 v50, 1.0, v50
	v_add_f32_e32 v51, 1.0, v51
	v_rcp_f32_e32 v50, v50
	v_rcp_f32_e32 v51, v51
	v_pk_fma_f32 v[48:49], v[48:49], 2.0, 1.0 op_sel_hi:[1,0,0] neg_lo:[1,0,0] neg_hi:[1,0,0]
	v_pk_mul_f32 v[44:45], v[44:45], 0.5 op_sel_hi:[1,0]
	v_pk_add_f32 v[48:49], v[48:49], 1.0 op_sel_hi:[1,0]
	v_pk_mul_f32 v[46:47], v[46:47], 0.5 op_sel_hi:[1,0]
	v_pk_mul_f32 v[44:45], v[44:45], v[48:49]
	v_pk_fma_f32 v[48:49], v[50:51], 2.0, 1.0 op_sel_hi:[1,0,0] neg_lo:[1,0,0] neg_hi:[1,0,0]
	v_cvt_pk_bf16_f32 v44, v44, v45
	v_pk_add_f32 v[48:49], v[48:49], 1.0 op_sel_hi:[1,0]
	s_nop 0
	v_pk_mul_f32 v[46:47], v[46:47], v[48:49]
	s_nop 0
	v_cvt_pk_bf16_f32 v45, v46, v47
	ds_write_b64 v101, v[44:45] offset:50048
	ds_read_b128 v[44:47], v100 offset:320
	ds_read_b128 v[48:51], v100 offset:16960
	ds_read_b128 v[52:55], v100 offset:33600
	s_waitcnt lgkmcnt(2)
; __device__ __forceinline__ u32x2 pack4(f32x4 v) { u32x2 r; r.x = cvt_pk_bf16(v[0], v[1]); r.y = cvt_pk_bf16(v[2], v[3]); return r; }
; __device__ __forceinline__ void compress_task(const Params& p, int task, char* smem) {
;     ...
; #pragma unroll
;         for (int nt = 0; nt < 16; ++nt) {
;             f32x4 v = acc[nt];
; #pragma unroll
;             for (int ww = 0; ww < 3; ++ww) v = v + *(const f32x4*)(red + (ww * 16 + fr) * 260 + nt * 16 + fq * 4);
; #pragma unroll
;             for (int j = 0; j < 4; ++j) v[j] = gelu_tanh(v[j]);
;             *(u32x2*)(hid + fr * 264 + nt * 16 + fq * 4) = pack4(v);
;         }
	v_pk_add_f32 v[40:41], v[40:41], v[44:45]
	s_waitcnt lgkmcnt(1)
	v_pk_add_f32 v[40:41], v[40:41], v[48:49]
	v_pk_add_f32 v[42:43], v[42:43], v[46:47]
	s_waitcnt lgkmcnt(0)
	v_pk_add_f32 v[40:41], v[40:41], v[52:53]
	v_pk_add_f32 v[42:43], v[42:43], v[50:51]
	v_mul_f32_e32 v44, 0x3d372713, v40
	v_mul_f32_e32 v45, 0x3d372713, v41
	v_mul_f32_e32 v44, v40, v44
	v_mul_f32_e32 v45, v41, v45
	v_pk_add_f32 v[42:43], v[42:43], v[54:55]
	v_fma_f32 v44, v40, v44, v40
	v_fma_f32 v45, v41, v45, v41
	v_mul_f32_e32 v46, 0x3d372713, v42
	v_mul_f32_e32 v47, 0x3d372713, v43
	v_mul_f32_e32 v44, 0x3f4c422a, v44
	v_mul_f32_e32 v45, 0x3f4c422a, v45
	v_mul_f32_e32 v46, v42, v46
	v_mul_f32_e32 v47, v43, v47
	v_add_f32_e32 v44, v44, v44
	v_add_f32_e32 v45, v45, v45
	v_fma_f32 v46, v42, v46, v42
	v_fma_f32 v47, v43, v47, v43
	v_mul_f32_e32 v44, 0x3fb8aa3b, v44
	v_mul_f32_e32 v45, 0x3fb8aa3b, v45
	v_mul_f32_e32 v46, 0x3f4c422a, v46
	v_mul_f32_e32 v47, 0x3f4c422a, v47
	v_exp_f32_e32 v44, v44
	v_exp_f32_e32 v45, v45
	v_add_f32_e32 v46, v46, v46
	v_add_f32_e32 v47, v47, v47
	v_mul_f32_e32 v46, 0x3fb8aa3b, v46
	v_mul_f32_e32 v47, 0x3fb8aa3b, v47
	v_exp_f32_e32 v46, v46
	v_exp_f32_e32 v47, v47
	v_add_f32_e32 v44, 1.0, v44
	v_add_f32_e32 v45, 1.0, v45
	v_rcp_f32_e32 v44, v44
	v_rcp_f32_e32 v45, v45
	v_add_f32_e32 v46, 1.0, v46
	v_add_f32_e32 v47, 1.0, v47
	v_rcp_f32_e32 v46, v46
	v_rcp_f32_e32 v47, v47
	v_pk_fma_f32 v[44:45], v[44:45], 2.0, 1.0 op_sel_hi:[1,0,0] neg_lo:[1,0,0] neg_hi:[1,0,0]
	v_pk_mul_f32 v[40:41], v[40:41], 0.5 op_sel_hi:[1,0]
	v_pk_add_f32 v[44:45], v[44:45], 1.0 op_sel_hi:[1,0]
	v_pk_mul_f32 v[42:43], v[42:43], 0.5 op_sel_hi:[1,0]
	v_pk_mul_f32 v[40:41], v[40:41], v[44:45]
	v_pk_fma_f32 v[44:45], v[46:47], 2.0, 1.0 op_sel_hi:[1,0,0] neg_lo:[1,0,0] neg_hi:[1,0,0]
	v_cvt_pk_bf16_f32 v40, v40, v41
	v_pk_add_f32 v[44:45], v[44:45], 1.0 op_sel_hi:[1,0]
	s_nop 0
	v_pk_mul_f32 v[42:43], v[42:43], v[44:45]
	s_nop 0
	v_cvt_pk_bf16_f32 v41, v42, v43
	ds_write_b64 v101, v[40:41] offset:50080
	ds_read_b128 v[40:43], v100 offset:384
	ds_read_b128 v[44:47], v100 offset:17024
	ds_read_b128 v[48:51], v100 offset:33664
	s_waitcnt lgkmcnt(2)
	v_pk_add_f32 v[36:37], v[36:37], v[40:41]
	s_waitcnt lgkmcnt(1)
	v_pk_add_f32 v[36:37], v[36:37], v[44:45]
	v_pk_add_f32 v[38:39], v[38:39], v[42:43]
	s_waitcnt lgkmcnt(0)
	v_pk_add_f32 v[36:37], v[36:37], v[48:49]
	v_pk_add_f32 v[38:39], v[38:39], v[46:47]
	v_mul_f32_e32 v40, 0x3d372713, v36
	v_mul_f32_e32 v41, 0x3d372713, v37
	v_mul_f32_e32 v40, v36, v40
	v_mul_f32_e32 v41, v37, v41
	v_pk_add_f32 v[38:39], v[38:39], v[50:51]
	v_fma_f32 v40, v36, v40, v36
	v_fma_f32 v41, v37, v41, v37
	v_mul_f32_e32 v42, 0x3d372713, v38
	v_mul_f32_e32 v43, 0x3d372713, v39
	v_mul_f32_e32 v40, 0x3f4c422a, v40
	v_mul_f32_e32 v41, 0x3f4c422a, v41
	v_mul_f32_e32 v42, v38, v42
	v_mul_f32_e32 v43, v39, v43
	v_add_f32_e32 v40, v40, v40
	v_add_f32_e32 v41, v41, v41
	v_fma_f32 v42, v38, v42, v38
	v_fma_f32 v43, v39, v43, v39
	v_mul_f32_e32 v40, 0x3fb8aa3b, v40
	v_mul_f32_e32 v41, 0x3fb8aa3b, v41
	v_mul_f32_e32 v42, 0x3f4c422a, v42
	v_mul_f32_e32 v43, 0x3f4c422a, v43
	v_exp_f32_e32 v40, v40
	v_exp_f32_e32 v41, v41
	v_add_f32_e32 v42, v42, v42
	v_add_f32_e32 v43, v43, v43
	v_mul_f32_e32 v42, 0x3fb8aa3b, v42
	v_mul_f32_e32 v43, 0x3fb8aa3b, v43
	v_exp_f32_e32 v42, v42
	v_exp_f32_e32 v43, v43
	v_add_f32_e32 v40, 1.0, v40
	v_add_f32_e32 v41, 1.0, v41
	v_rcp_f32_e32 v40, v40
	v_rcp_f32_e32 v41, v41
	v_add_f32_e32 v42, 1.0, v42
	v_add_f32_e32 v43, 1.0, v43
	v_rcp_f32_e32 v42, v42
	v_rcp_f32_e32 v43, v43
	v_pk_fma_f32 v[40:41], v[40:41], 2.0, 1.0 op_sel_hi:[1,0,0] neg_lo:[1,0,0] neg_hi:[1,0,0]
	v_pk_mul_f32 v[36:37], v[36:37], 0.5 op_sel_hi:[1,0]
	v_pk_add_f32 v[40:41], v[40:41], 1.0 op_sel_hi:[1,0]
	v_pk_mul_f32 v[38:39], v[38:39], 0.5 op_sel_hi:[1,0]
	v_pk_mul_f32 v[36:37], v[36:37], v[40:41]
	v_pk_fma_f32 v[40:41], v[42:43], 2.0, 1.0 op_sel_hi:[1,0,0] neg_lo:[1,0,0] neg_hi:[1,0,0]
	v_cvt_pk_bf16_f32 v36, v36, v37
	v_pk_add_f32 v[40:41], v[40:41], 1.0 op_sel_hi:[1,0]
	s_nop 0
	v_pk_mul_f32 v[38:39], v[38:39], v[40:41]
	s_nop 0
	v_cvt_pk_bf16_f32 v37, v38, v39
	ds_write_b64 v101, v[36:37] offset:50112
	ds_read_b128 v[36:39], v100 offset:448
	ds_read_b128 v[40:43], v100 offset:17088
	ds_read_b128 v[44:47], v100 offset:33728
	s_waitcnt lgkmcnt(2)
	v_pk_add_f32 v[32:33], v[32:33], v[36:37]
	s_waitcnt lgkmcnt(1)
	v_pk_add_f32 v[32:33], v[32:33], v[40:41]
	v_pk_add_f32 v[34:35], v[34:35], v[38:39]
	s_waitcnt lgkmcnt(0)
	v_pk_add_f32 v[32:33], v[32:33], v[44:45]
	v_pk_add_f32 v[34:35], v[34:35], v[42:43]
	v_mul_f32_e32 v36, 0x3d372713, v32
	v_mul_f32_e32 v37, 0x3d372713, v33
	v_mul_f32_e32 v36, v32, v36
	v_mul_f32_e32 v37, v33, v37
	v_pk_add_f32 v[34:35], v[34:35], v[46:47]
	v_fma_f32 v36, v32, v36, v32
	v_fma_f32 v37, v33, v37, v33
	v_mul_f32_e32 v38, 0x3d372713, v34
	v_mul_f32_e32 v39, 0x3d372713, v35
	v_mul_f32_e32 v36, 0x3f4c422a, v36
	v_mul_f32_e32 v37, 0x3f4c422a, v37
	v_mul_f32_e32 v38, v34, v38
	v_mul_f32_e32 v39, v35, v39
	v_add_f32_e32 v36, v36, v36
	v_add_f32_e32 v37, v37, v37
	v_fma_f32 v38, v34, v38, v34
	v_fma_f32 v39, v35, v39, v35
	v_mul_f32_e32 v36, 0x3fb8aa3b, v36
	v_mul_f32_e32 v37, 0x3fb8aa3b, v37
	v_mul_f32_e32 v38, 0x3f4c422a, v38
	v_mul_f32_e32 v39, 0x3f4c422a, v39
	v_exp_f32_e32 v36, v36
	v_exp_f32_e32 v37, v37
	v_add_f32_e32 v38, v38, v38
	v_add_f32_e32 v39, v39, v39
	v_mul_f32_e32 v38, 0x3fb8aa3b, v38
	v_mul_f32_e32 v39, 0x3fb8aa3b, v39
	v_exp_f32_e32 v38, v38
	v_exp_f32_e32 v39, v39
	v_add_f32_e32 v36, 1.0, v36
	v_add_f32_e32 v37, 1.0, v37
	v_rcp_f32_e32 v36, v36
	v_rcp_f32_e32 v37, v37
	v_add_f32_e32 v38, 1.0, v38
	v_add_f32_e32 v39, 1.0, v39
	v_rcp_f32_e32 v38, v38
	v_rcp_f32_e32 v39, v39
	v_pk_fma_f32 v[36:37], v[36:37], 2.0, 1.0 op_sel_hi:[1,0,0] neg_lo:[1,0,0] neg_hi:[1,0,0]
	v_pk_mul_f32 v[32:33], v[32:33], 0.5 op_sel_hi:[1,0]
	v_pk_add_f32 v[36:37], v[36:37], 1.0 op_sel_hi:[1,0]
	v_pk_mul_f32 v[34:35], v[34:35], 0.5 op_sel_hi:[1,0]
	v_pk_mul_f32 v[32:33], v[32:33], v[36:37]
	v_pk_fma_f32 v[36:37], v[38:39], 2.0, 1.0 op_sel_hi:[1,0,0] neg_lo:[1,0,0] neg_hi:[1,0,0]
	v_cvt_pk_bf16_f32 v32, v32, v33
	v_pk_add_f32 v[36:37], v[36:37], 1.0 op_sel_hi:[1,0]
	s_nop 0
	v_pk_mul_f32 v[34:35], v[34:35], v[36:37]
	s_nop 0
	v_cvt_pk_bf16_f32 v33, v34, v35
	ds_write_b64 v101, v[32:33] offset:50144
	ds_read_b128 v[32:35], v100 offset:512
	ds_read_b128 v[36:39], v100 offset:17152
	ds_read_b128 v[40:43], v100 offset:33792
	s_waitcnt lgkmcnt(2)
; __device__ __forceinline__ u32x2 pack4(f32x4 v) { u32x2 r; r.x = cvt_pk_bf16(v[0], v[1]); r.y = cvt_pk_bf16(v[2], v[3]); return r; }
; __device__ __forceinline__ void compress_task(const Params& p, int task, char* smem) {
;     ...
; #pragma unroll
;         for (int nt = 0; nt < 16; ++nt) {
;             f32x4 v = acc[nt];
; #pragma unroll
;             for (int ww = 0; ww < 3; ++ww) v = v + *(const f32x4*)(red + (ww * 16 + fr) * 260 + nt * 16 + fq * 4);
; #pragma unroll
;             for (int j = 0; j < 4; ++j) v[j] = gelu_tanh(v[j]);
;             *(u32x2*)(hid + fr * 264 + nt * 16 + fq * 4) = pack4(v);
;         }
	v_pk_add_f32 v[28:29], v[28:29], v[32:33]
	s_waitcnt lgkmcnt(1)
	v_pk_add_f32 v[28:29], v[28:29], v[36:37]
	v_pk_add_f32 v[30:31], v[30:31], v[34:35]
	s_waitcnt lgkmcnt(0)
	v_pk_add_f32 v[28:29], v[28:29], v[40:41]
	v_pk_add_f32 v[30:31], v[30:31], v[38:39]
	v_mul_f32_e32 v32, 0x3d372713, v28
	v_mul_f32_e32 v33, 0x3d372713, v29
	v_mul_f32_e32 v32, v28, v32
	v_mul_f32_e32 v33, v29, v33
	v_pk_add_f32 v[30:31], v[30:31], v[42:43]
	v_fma_f32 v32, v28, v32, v28
	v_fma_f32 v33, v29, v33, v29
	v_mul_f32_e32 v34, 0x3d372713, v30
	v_mul_f32_e32 v35, 0x3d372713, v31
	v_mul_f32_e32 v32, 0x3f4c422a, v32
	v_mul_f32_e32 v33, 0x3f4c422a, v33
	v_mul_f32_e32 v34, v30, v34
	v_mul_f32_e32 v35, v31, v35
	v_add_f32_e32 v32, v32, v32
	v_add_f32_e32 v33, v33, v33
	v_fma_f32 v34, v30, v34, v30
	v_fma_f32 v35, v31, v35, v31
	v_mul_f32_e32 v32, 0x3fb8aa3b, v32
	v_mul_f32_e32 v33, 0x3fb8aa3b, v33
	v_mul_f32_e32 v34, 0x3f4c422a, v34
	v_mul_f32_e32 v35, 0x3f4c422a, v35
	v_exp_f32_e32 v32, v32
	v_exp_f32_e32 v33, v33
	v_add_f32_e32 v34, v34, v34
	v_add_f32_e32 v35, v35, v35
	v_mul_f32_e32 v34, 0x3fb8aa3b, v34
	v_mul_f32_e32 v35, 0x3fb8aa3b, v35
	v_exp_f32_e32 v34, v34
	v_exp_f32_e32 v35, v35
	v_add_f32_e32 v32, 1.0, v32
	v_add_f32_e32 v33, 1.0, v33
	v_rcp_f32_e32 v32, v32
	v_rcp_f32_e32 v33, v33
	v_add_f32_e32 v34, 1.0, v34
	v_add_f32_e32 v35, 1.0, v35
	v_rcp_f32_e32 v34, v34
	v_rcp_f32_e32 v35, v35
	v_pk_fma_f32 v[32:33], v[32:33], 2.0, 1.0 op_sel_hi:[1,0,0] neg_lo:[1,0,0] neg_hi:[1,0,0]
	v_pk_mul_f32 v[28:29], v[28:29], 0.5 op_sel_hi:[1,0]
	v_pk_add_f32 v[32:33], v[32:33], 1.0 op_sel_hi:[1,0]
	v_pk_mul_f32 v[30:31], v[30:31], 0.5 op_sel_hi:[1,0]
	v_pk_mul_f32 v[28:29], v[28:29], v[32:33]
	v_pk_fma_f32 v[32:33], v[34:35], 2.0, 1.0 op_sel_hi:[1,0,0] neg_lo:[1,0,0] neg_hi:[1,0,0]
	v_cvt_pk_bf16_f32 v28, v28, v29
	v_pk_add_f32 v[32:33], v[32:33], 1.0 op_sel_hi:[1,0]
	s_nop 0
	v_pk_mul_f32 v[30:31], v[30:31], v[32:33]
	s_nop 0
	v_cvt_pk_bf16_f32 v29, v30, v31
	ds_write_b64 v101, v[28:29] offset:50176
	ds_read_b128 v[28:31], v100 offset:576
	ds_read_b128 v[32:35], v100 offset:17216
	ds_read_b128 v[36:39], v100 offset:33856
	s_waitcnt lgkmcnt(2)
	v_pk_add_f32 v[24:25], v[24:25], v[28:29]
	s_waitcnt lgkmcnt(1)
	v_pk_add_f32 v[24:25], v[24:25], v[32:33]
	v_pk_add_f32 v[26:27], v[26:27], v[30:31]
	s_waitcnt lgkmcnt(0)
	v_pk_add_f32 v[24:25], v[24:25], v[36:37]
	v_pk_add_f32 v[26:27], v[26:27], v[34:35]
	v_mul_f32_e32 v28, 0x3d372713, v24
	v_mul_f32_e32 v29, 0x3d372713, v25
	v_mul_f32_e32 v28, v24, v28
	v_mul_f32_e32 v29, v25, v29
	v_pk_add_f32 v[26:27], v[26:27], v[38:39]
	v_fma_f32 v28, v24, v28, v24
	v_fma_f32 v29, v25, v29, v25
	v_mul_f32_e32 v30, 0x3d372713, v26
	v_mul_f32_e32 v31, 0x3d372713, v27
	v_mul_f32_e32 v28, 0x3f4c422a, v28
	v_mul_f32_e32 v29, 0x3f4c422a, v29
	v_mul_f32_e32 v30, v26, v30
	v_mul_f32_e32 v31, v27, v31
	v_add_f32_e32 v28, v28, v28
	v_add_f32_e32 v29, v29, v29
	v_fma_f32 v30, v26, v30, v26
	v_fma_f32 v31, v27, v31, v27
	v_mul_f32_e32 v28, 0x3fb8aa3b, v28
	v_mul_f32_e32 v29, 0x3fb8aa3b, v29
	v_mul_f32_e32 v30, 0x3f4c422a, v30
	v_mul_f32_e32 v31, 0x3f4c422a, v31
	v_exp_f32_e32 v28, v28
	v_exp_f32_e32 v29, v29
	v_add_f32_e32 v30, v30, v30
	v_add_f32_e32 v31, v31, v31
	v_mul_f32_e32 v30, 0x3fb8aa3b, v30
	v_mul_f32_e32 v31, 0x3fb8aa3b, v31
	v_exp_f32_e32 v30, v30
	v_exp_f32_e32 v31, v31
	v_add_f32_e32 v28, 1.0, v28
	v_add_f32_e32 v29, 1.0, v29
	v_rcp_f32_e32 v28, v28
	v_rcp_f32_e32 v29, v29
	v_add_f32_e32 v30, 1.0, v30
	v_add_f32_e32 v31, 1.0, v31
	v_rcp_f32_e32 v30, v30
	v_rcp_f32_e32 v31, v31
	v_pk_fma_f32 v[28:29], v[28:29], 2.0, 1.0 op_sel_hi:[1,0,0] neg_lo:[1,0,0] neg_hi:[1,0,0]
	v_pk_mul_f32 v[24:25], v[24:25], 0.5 op_sel_hi:[1,0]
	v_pk_add_f32 v[28:29], v[28:29], 1.0 op_sel_hi:[1,0]
	v_pk_mul_f32 v[26:27], v[26:27], 0.5 op_sel_hi:[1,0]
	v_pk_mul_f32 v[24:25], v[24:25], v[28:29]
	v_pk_fma_f32 v[28:29], v[30:31], 2.0, 1.0 op_sel_hi:[1,0,0] neg_lo:[1,0,0] neg_hi:[1,0,0]
	v_cvt_pk_bf16_f32 v24, v24, v25
	v_pk_add_f32 v[28:29], v[28:29], 1.0 op_sel_hi:[1,0]
	s_nop 0
	v_pk_mul_f32 v[26:27], v[26:27], v[28:29]
	s_nop 0
	v_cvt_pk_bf16_f32 v25, v26, v27
	ds_write_b64 v101, v[24:25] offset:50208
	ds_read_b128 v[24:27], v100 offset:640
	ds_read_b128 v[28:31], v100 offset:17280
	ds_read_b128 v[32:35], v100 offset:33920
	s_waitcnt lgkmcnt(2)
	v_pk_add_f32 v[20:21], v[20:21], v[24:25]
	s_waitcnt lgkmcnt(1)
	v_pk_add_f32 v[20:21], v[20:21], v[28:29]
	v_pk_add_f32 v[22:23], v[22:23], v[26:27]
	s_waitcnt lgkmcnt(0)
	v_pk_add_f32 v[20:21], v[20:21], v[32:33]
	v_pk_add_f32 v[22:23], v[22:23], v[30:31]
	v_mul_f32_e32 v24, 0x3d372713, v20
	v_mul_f32_e32 v25, 0x3d372713, v21
	v_mul_f32_e32 v24, v20, v24
	v_mul_f32_e32 v25, v21, v25
	v_pk_add_f32 v[22:23], v[22:23], v[34:35]
	v_fma_f32 v24, v20, v24, v20
	v_fma_f32 v25, v21, v25, v21
	v_mul_f32_e32 v26, 0x3d372713, v22
	v_mul_f32_e32 v27, 0x3d372713, v23
	v_mul_f32_e32 v24, 0x3f4c422a, v24
	v_mul_f32_e32 v25, 0x3f4c422a, v25
	v_mul_f32_e32 v26, v22, v26
	v_mul_f32_e32 v27, v23, v27
	v_add_f32_e32 v24, v24, v24
	v_add_f32_e32 v25, v25, v25
	v_fma_f32 v26, v22, v26, v22
	v_fma_f32 v27, v23, v27, v23
	v_mul_f32_e32 v24, 0x3fb8aa3b, v24
	v_mul_f32_e32 v25, 0x3fb8aa3b, v25
	v_mul_f32_e32 v26, 0x3f4c422a, v26
	v_mul_f32_e32 v27, 0x3f4c422a, v27
	v_exp_f32_e32 v24, v24
	v_exp_f32_e32 v25, v25
	v_add_f32_e32 v26, v26, v26
	v_add_f32_e32 v27, v27, v27
	v_mul_f32_e32 v26, 0x3fb8aa3b, v26
	v_mul_f32_e32 v27, 0x3fb8aa3b, v27
	v_exp_f32_e32 v26, v26
	v_exp_f32_e32 v27, v27
	v_add_f32_e32 v24, 1.0, v24
	v_add_f32_e32 v25, 1.0, v25
	v_rcp_f32_e32 v24, v24
	v_rcp_f32_e32 v25, v25
	v_add_f32_e32 v26, 1.0, v26
	v_add_f32_e32 v27, 1.0, v27
	v_rcp_f32_e32 v26, v26
	v_rcp_f32_e32 v27, v27
	v_pk_fma_f32 v[24:25], v[24:25], 2.0, 1.0 op_sel_hi:[1,0,0] neg_lo:[1,0,0] neg_hi:[1,0,0]
	v_pk_mul_f32 v[20:21], v[20:21], 0.5 op_sel_hi:[1,0]
	v_pk_add_f32 v[24:25], v[24:25], 1.0 op_sel_hi:[1,0]
	v_pk_mul_f32 v[22:23], v[22:23], 0.5 op_sel_hi:[1,0]
	v_pk_mul_f32 v[20:21], v[20:21], v[24:25]
	v_pk_fma_f32 v[24:25], v[26:27], 2.0, 1.0 op_sel_hi:[1,0,0] neg_lo:[1,0,0] neg_hi:[1,0,0]
	v_cvt_pk_bf16_f32 v20, v20, v21
	v_pk_add_f32 v[24:25], v[24:25], 1.0 op_sel_hi:[1,0]
	s_nop 0
	v_pk_mul_f32 v[22:23], v[22:23], v[24:25]
	s_nop 0
	v_cvt_pk_bf16_f32 v21, v22, v23
	ds_write_b64 v101, v[20:21] offset:50240
	ds_read_b128 v[20:23], v100 offset:704
	ds_read_b128 v[24:27], v100 offset:17344
	ds_read_b128 v[28:31], v100 offset:33984
	s_waitcnt lgkmcnt(2)
; __device__ __forceinline__ u32x2 pack4(f32x4 v) { u32x2 r; r.x = cvt_pk_bf16(v[0], v[1]); r.y = cvt_pk_bf16(v[2], v[3]); return r; }
; __device__ __forceinline__ void compress_task(const Params& p, int task, char* smem) {
;     ...
; #pragma unroll
;         for (int nt = 0; nt < 16; ++nt) {
;             f32x4 v = acc[nt];
; #pragma unroll
;             for (int ww = 0; ww < 3; ++ww) v = v + *(const f32x4*)(red + (ww * 16 + fr) * 260 + nt * 16 + fq * 4);
; #pragma unroll
;             for (int j = 0; j < 4; ++j) v[j] = gelu_tanh(v[j]);
;             *(u32x2*)(hid + fr * 264 + nt * 16 + fq * 4) = pack4(v);
;         }
	v_pk_add_f32 v[16:17], v[16:17], v[20:21]
	s_waitcnt lgkmcnt(1)
	v_pk_add_f32 v[16:17], v[16:17], v[24:25]
	v_pk_add_f32 v[18:19], v[18:19], v[22:23]
	s_waitcnt lgkmcnt(0)
	v_pk_add_f32 v[16:17], v[16:17], v[28:29]
	v_pk_add_f32 v[18:19], v[18:19], v[26:27]
	v_mul_f32_e32 v20, 0x3d372713, v16
	v_mul_f32_e32 v21, 0x3d372713, v17
	v_mul_f32_e32 v20, v16, v20
	v_mul_f32_e32 v21, v17, v21
	v_pk_add_f32 v[18:19], v[18:19], v[30:31]
	v_fma_f32 v20, v16, v20, v16
	v_fma_f32 v21, v17, v21, v17
	v_mul_f32_e32 v22, 0x3d372713, v18
	v_mul_f32_e32 v23, 0x3d372713, v19
	v_mul_f32_e32 v20, 0x3f4c422a, v20
	v_mul_f32_e32 v21, 0x3f4c422a, v21
	v_mul_f32_e32 v22, v18, v22
	v_mul_f32_e32 v23, v19, v23
	v_add_f32_e32 v20, v20, v20
	v_add_f32_e32 v21, v21, v21
	v_fma_f32 v22, v18, v22, v18
	v_fma_f32 v23, v19, v23, v19
	v_mul_f32_e32 v20, 0x3fb8aa3b, v20
	v_mul_f32_e32 v21, 0x3fb8aa3b, v21
	v_mul_f32_e32 v22, 0x3f4c422a, v22
	v_mul_f32_e32 v23, 0x3f4c422a, v23
	v_exp_f32_e32 v20, v20
	v_exp_f32_e32 v21, v21
	v_add_f32_e32 v22, v22, v22
	v_add_f32_e32 v23, v23, v23
	v_mul_f32_e32 v22, 0x3fb8aa3b, v22
	v_mul_f32_e32 v23, 0x3fb8aa3b, v23
	v_exp_f32_e32 v22, v22
	v_exp_f32_e32 v23, v23
	v_add_f32_e32 v20, 1.0, v20
	v_add_f32_e32 v21, 1.0, v21
	v_rcp_f32_e32 v20, v20
	v_rcp_f32_e32 v21, v21
	v_add_f32_e32 v22, 1.0, v22
	v_add_f32_e32 v23, 1.0, v23
	v_rcp_f32_e32 v22, v22
	v_rcp_f32_e32 v23, v23
	v_pk_fma_f32 v[20:21], v[20:21], 2.0, 1.0 op_sel_hi:[1,0,0] neg_lo:[1,0,0] neg_hi:[1,0,0]
	v_pk_mul_f32 v[16:17], v[16:17], 0.5 op_sel_hi:[1,0]
	v_pk_add_f32 v[20:21], v[20:21], 1.0 op_sel_hi:[1,0]
	v_pk_mul_f32 v[18:19], v[18:19], 0.5 op_sel_hi:[1,0]
	v_pk_mul_f32 v[16:17], v[16:17], v[20:21]
	v_pk_fma_f32 v[20:21], v[22:23], 2.0, 1.0 op_sel_hi:[1,0,0] neg_lo:[1,0,0] neg_hi:[1,0,0]
	v_cvt_pk_bf16_f32 v16, v16, v17
	v_pk_add_f32 v[20:21], v[20:21], 1.0 op_sel_hi:[1,0]
	s_nop 0
	v_pk_mul_f32 v[18:19], v[18:19], v[20:21]
	s_nop 0
	v_cvt_pk_bf16_f32 v17, v18, v19
	ds_write_b64 v101, v[16:17] offset:50272
	ds_read_b128 v[16:19], v100 offset:768
	ds_read_b128 v[20:23], v100 offset:17408
	ds_read_b128 v[24:27], v100 offset:34048
	s_waitcnt lgkmcnt(2)
	v_pk_add_f32 v[12:13], v[12:13], v[16:17]
	s_waitcnt lgkmcnt(1)
	v_pk_add_f32 v[12:13], v[12:13], v[20:21]
	v_pk_add_f32 v[14:15], v[14:15], v[18:19]
	s_waitcnt lgkmcnt(0)
	v_pk_add_f32 v[12:13], v[12:13], v[24:25]
	v_pk_add_f32 v[14:15], v[14:15], v[22:23]
	v_mul_f32_e32 v16, 0x3d372713, v12
	v_mul_f32_e32 v17, 0x3d372713, v13
	v_mul_f32_e32 v16, v12, v16
	v_mul_f32_e32 v17, v13, v17
	v_pk_add_f32 v[14:15], v[14:15], v[26:27]
	v_fma_f32 v16, v12, v16, v12
	v_fma_f32 v17, v13, v17, v13
	v_mul_f32_e32 v18, 0x3d372713, v14
	v_mul_f32_e32 v19, 0x3d372713, v15
	v_mul_f32_e32 v16, 0x3f4c422a, v16
	v_mul_f32_e32 v17, 0x3f4c422a, v17
	v_mul_f32_e32 v18, v14, v18
	v_mul_f32_e32 v19, v15, v19
	v_add_f32_e32 v16, v16, v16
	v_add_f32_e32 v17, v17, v17
	v_fma_f32 v18, v14, v18, v14
	v_fma_f32 v19, v15, v19, v15
	v_mul_f32_e32 v16, 0x3fb8aa3b, v16
	v_mul_f32_e32 v17, 0x3fb8aa3b, v17
	v_mul_f32_e32 v18, 0x3f4c422a, v18
	v_mul_f32_e32 v19, 0x3f4c422a, v19
	v_exp_f32_e32 v16, v16
	v_exp_f32_e32 v17, v17
	v_add_f32_e32 v18, v18, v18
	v_add_f32_e32 v19, v19, v19
	v_mul_f32_e32 v18, 0x3fb8aa3b, v18
	v_mul_f32_e32 v19, 0x3fb8aa3b, v19
	v_exp_f32_e32 v18, v18
	v_exp_f32_e32 v19, v19
	v_add_f32_e32 v16, 1.0, v16
	v_add_f32_e32 v17, 1.0, v17
	v_rcp_f32_e32 v16, v16
	v_rcp_f32_e32 v17, v17
	v_add_f32_e32 v18, 1.0, v18
	v_add_f32_e32 v19, 1.0, v19
	v_rcp_f32_e32 v18, v18
	v_rcp_f32_e32 v19, v19
	v_pk_fma_f32 v[16:17], v[16:17], 2.0, 1.0 op_sel_hi:[1,0,0] neg_lo:[1,0,0] neg_hi:[1,0,0]
	v_pk_mul_f32 v[12:13], v[12:13], 0.5 op_sel_hi:[1,0]
	v_pk_add_f32 v[16:17], v[16:17], 1.0 op_sel_hi:[1,0]
	v_pk_mul_f32 v[14:15], v[14:15], 0.5 op_sel_hi:[1,0]
	v_pk_mul_f32 v[12:13], v[12:13], v[16:17]
	v_pk_fma_f32 v[16:17], v[18:19], 2.0, 1.0 op_sel_hi:[1,0,0] neg_lo:[1,0,0] neg_hi:[1,0,0]
	v_cvt_pk_bf16_f32 v12, v12, v13
	v_pk_add_f32 v[16:17], v[16:17], 1.0 op_sel_hi:[1,0]
	s_nop 0
	v_pk_mul_f32 v[14:15], v[14:15], v[16:17]
	s_nop 0
	v_cvt_pk_bf16_f32 v13, v14, v15
	ds_write_b64 v101, v[12:13] offset:50304
	ds_read_b128 v[12:15], v100 offset:832
	ds_read_b128 v[16:19], v100 offset:17472
	ds_read_b128 v[20:23], v100 offset:34112
	s_waitcnt lgkmcnt(2)
	v_pk_add_f32 v[8:9], v[8:9], v[12:13]
	s_waitcnt lgkmcnt(1)
	v_pk_add_f32 v[8:9], v[8:9], v[16:17]
	v_pk_add_f32 v[10:11], v[10:11], v[14:15]
	s_waitcnt lgkmcnt(0)
; __device__ __forceinline__ u32x2 pack4(f32x4 v) { u32x2 r; r.x = cvt_pk_bf16(v[0], v[1]); r.y = cvt_pk_bf16(v[2], v[3]); return r; }
; __device__ __forceinline__ void compress_task(const Params& p, int task, char* smem) {
;     ...
; #pragma unroll
;         for (int nt = 0; nt < 16; ++nt) {
;             f32x4 v = acc[nt];
; #pragma unroll
;             for (int ww = 0; ww < 3; ++ww) v = v + *(const f32x4*)(red + (ww * 16 + fr) * 260 + nt * 16 + fq * 4);
; #pragma unroll
;             for (int j = 0; j < 4; ++j) v[j] = gelu_tanh(v[j]);
;             *(u32x2*)(hid + fr * 264 + nt * 16 + fq * 4) = pack4(v);
;         }
	v_pk_add_f32 v[8:9], v[8:9], v[20:21]
	v_pk_add_f32 v[10:11], v[10:11], v[18:19]
	v_mul_f32_e32 v12, 0x3d372713, v8
	v_mul_f32_e32 v13, 0x3d372713, v9
	v_mul_f32_e32 v12, v8, v12
	v_mul_f32_e32 v13, v9, v13
	v_pk_add_f32 v[10:11], v[10:11], v[22:23]
	v_fma_f32 v12, v8, v12, v8
	v_fma_f32 v13, v9, v13, v9
	v_mul_f32_e32 v14, 0x3d372713, v10
	v_mul_f32_e32 v15, 0x3d372713, v11
	v_mul_f32_e32 v12, 0x3f4c422a, v12
	v_mul_f32_e32 v13, 0x3f4c422a, v13
	v_mul_f32_e32 v14, v10, v14
	v_mul_f32_e32 v15, v11, v15
	v_add_f32_e32 v12, v12, v12
	v_add_f32_e32 v13, v13, v13
	v_fma_f32 v14, v10, v14, v10
	v_fma_f32 v15, v11, v15, v11
	v_mul_f32_e32 v12, 0x3fb8aa3b, v12
	v_mul_f32_e32 v13, 0x3fb8aa3b, v13
	v_mul_f32_e32 v14, 0x3f4c422a, v14
	v_mul_f32_e32 v15, 0x3f4c422a, v15
	v_exp_f32_e32 v12, v12
	v_exp_f32_e32 v13, v13
	v_add_f32_e32 v14, v14, v14
	v_add_f32_e32 v15, v15, v15
	v_mul_f32_e32 v14, 0x3fb8aa3b, v14
	v_mul_f32_e32 v15, 0x3fb8aa3b, v15
	v_exp_f32_e32 v14, v14
	v_exp_f32_e32 v15, v15
	v_add_f32_e32 v12, 1.0, v12
	v_add_f32_e32 v13, 1.0, v13
	v_rcp_f32_e32 v12, v12
	v_rcp_f32_e32 v13, v13
	v_add_f32_e32 v14, 1.0, v14
	v_add_f32_e32 v15, 1.0, v15
	v_rcp_f32_e32 v14, v14
	v_rcp_f32_e32 v15, v15
	v_pk_fma_f32 v[12:13], v[12:13], 2.0, 1.0 op_sel_hi:[1,0,0] neg_lo:[1,0,0] neg_hi:[1,0,0]
	v_pk_mul_f32 v[8:9], v[8:9], 0.5 op_sel_hi:[1,0]
	v_pk_add_f32 v[12:13], v[12:13], 1.0 op_sel_hi:[1,0]
	v_pk_mul_f32 v[10:11], v[10:11], 0.5 op_sel_hi:[1,0]
	v_pk_mul_f32 v[8:9], v[8:9], v[12:13]
	v_pk_fma_f32 v[12:13], v[14:15], 2.0, 1.0 op_sel_hi:[1,0,0] neg_lo:[1,0,0] neg_hi:[1,0,0]
	v_cvt_pk_bf16_f32 v8, v8, v9
	v_pk_add_f32 v[12:13], v[12:13], 1.0 op_sel_hi:[1,0]
	s_nop 0
	v_pk_mul_f32 v[10:11], v[10:11], v[12:13]
	s_nop 0
	v_cvt_pk_bf16_f32 v9, v10, v11
	ds_write_b64 v101, v[8:9] offset:50336
	ds_read_b128 v[8:11], v100 offset:896
	ds_read_b128 v[12:15], v100 offset:17536
	ds_read_b128 v[16:19], v100 offset:34176
	s_waitcnt lgkmcnt(2)
	v_pk_add_f32 v[4:5], v[4:5], v[8:9]
	s_waitcnt lgkmcnt(1)
	v_pk_add_f32 v[4:5], v[4:5], v[12:13]
	v_pk_add_f32 v[6:7], v[6:7], v[10:11]
	s_waitcnt lgkmcnt(0)
	v_pk_add_f32 v[4:5], v[4:5], v[16:17]
	v_pk_add_f32 v[6:7], v[6:7], v[14:15]
	v_mul_f32_e32 v8, 0x3d372713, v4
	v_mul_f32_e32 v9, 0x3d372713, v5
	v_mul_f32_e32 v8, v4, v8
	v_mul_f32_e32 v9, v5, v9
	v_pk_add_f32 v[6:7], v[6:7], v[18:19]
	v_fma_f32 v8, v4, v8, v4
	v_fma_f32 v9, v5, v9, v5
	v_mul_f32_e32 v10, 0x3d372713, v6
	v_mul_f32_e32 v11, 0x3d372713, v7
	v_mul_f32_e32 v8, 0x3f4c422a, v8
	v_mul_f32_e32 v9, 0x3f4c422a, v9
	v_mul_f32_e32 v10, v6, v10
	v_mul_f32_e32 v11, v7, v11
	v_add_f32_e32 v8, v8, v8
	v_add_f32_e32 v9, v9, v9
	v_fma_f32 v10, v6, v10, v6
	v_fma_f32 v11, v7, v11, v7
	v_mul_f32_e32 v8, 0x3fb8aa3b, v8
	v_mul_f32_e32 v9, 0x3fb8aa3b, v9
	v_mul_f32_e32 v10, 0x3f4c422a, v10
	v_mul_f32_e32 v11, 0x3f4c422a, v11
	v_exp_f32_e32 v8, v8
	v_exp_f32_e32 v9, v9
	v_add_f32_e32 v10, v10, v10
	v_add_f32_e32 v11, v11, v11
	v_mul_f32_e32 v10, 0x3fb8aa3b, v10
	v_mul_f32_e32 v11, 0x3fb8aa3b, v11
	v_exp_f32_e32 v10, v10
	v_exp_f32_e32 v11, v11
	v_add_f32_e32 v8, 1.0, v8
	v_add_f32_e32 v9, 1.0, v9
	v_rcp_f32_e32 v8, v8
	v_rcp_f32_e32 v9, v9
	v_add_f32_e32 v10, 1.0, v10
	v_add_f32_e32 v11, 1.0, v11
	v_rcp_f32_e32 v10, v10
	v_rcp_f32_e32 v11, v11
	v_pk_fma_f32 v[8:9], v[8:9], 2.0, 1.0 op_sel_hi:[1,0,0] neg_lo:[1,0,0] neg_hi:[1,0,0]
	v_pk_mul_f32 v[4:5], v[4:5], 0.5 op_sel_hi:[1,0]
	v_pk_add_f32 v[8:9], v[8:9], 1.0 op_sel_hi:[1,0]
	v_pk_mul_f32 v[6:7], v[6:7], 0.5 op_sel_hi:[1,0]
	v_pk_mul_f32 v[4:5], v[4:5], v[8:9]
	v_pk_fma_f32 v[8:9], v[10:11], 2.0, 1.0 op_sel_hi:[1,0,0] neg_lo:[1,0,0] neg_hi:[1,0,0]
	v_cvt_pk_bf16_f32 v4, v4, v5
	v_pk_add_f32 v[8:9], v[8:9], 1.0 op_sel_hi:[1,0]
	s_nop 0
	v_pk_mul_f32 v[6:7], v[6:7], v[8:9]
	s_nop 0
	v_cvt_pk_bf16_f32 v5, v6, v7
	ds_write_b64 v101, v[4:5] offset:50368
	ds_read_b128 v[4:7], v100 offset:960
	ds_read_b128 v[8:11], v100 offset:17600
	ds_read_b128 v[12:15], v100 offset:34240
	s_waitcnt lgkmcnt(2)
	v_pk_add_f32 v[0:1], v[0:1], v[4:5]
	s_waitcnt lgkmcnt(1)
	v_pk_add_f32 v[0:1], v[0:1], v[8:9]
	v_pk_add_f32 v[2:3], v[2:3], v[6:7]
	s_waitcnt lgkmcnt(0)
	v_pk_add_f32 v[0:1], v[0:1], v[12:13]
	v_pk_add_f32 v[2:3], v[2:3], v[10:11]
	v_mul_f32_e32 v4, 0x3d372713, v0
	v_mul_f32_e32 v5, 0x3d372713, v1
	v_mul_f32_e32 v4, v0, v4
	v_mul_f32_e32 v5, v1, v5
	v_pk_add_f32 v[2:3], v[2:3], v[14:15]
	v_fma_f32 v4, v0, v4, v0
	v_fma_f32 v5, v1, v5, v1
	v_mul_f32_e32 v6, 0x3d372713, v2
	v_mul_f32_e32 v7, 0x3d372713, v3
	v_mul_f32_e32 v4, 0x3f4c422a, v4
	v_mul_f32_e32 v5, 0x3f4c422a, v5
	v_mul_f32_e32 v6, v2, v6
	v_mul_f32_e32 v7, v3, v7
	v_add_f32_e32 v4, v4, v4
	v_add_f32_e32 v5, v5, v5
	v_fma_f32 v6, v2, v6, v2
	v_fma_f32 v7, v3, v7, v3
	v_mul_f32_e32 v4, 0x3fb8aa3b, v4
	v_mul_f32_e32 v5, 0x3fb8aa3b, v5
	v_mul_f32_e32 v6, 0x3f4c422a, v6
	v_mul_f32_e32 v7, 0x3f4c422a, v7
	v_exp_f32_e32 v4, v4
	v_exp_f32_e32 v5, v5
	v_add_f32_e32 v6, v6, v6
	v_add_f32_e32 v7, v7, v7
	v_mul_f32_e32 v6, 0x3fb8aa3b, v6
	v_mul_f32_e32 v7, 0x3fb8aa3b, v7
	v_exp_f32_e32 v6, v6
	v_exp_f32_e32 v7, v7
	v_add_f32_e32 v4, 1.0, v4
	v_add_f32_e32 v5, 1.0, v5
	v_rcp_f32_e32 v4, v4
	v_rcp_f32_e32 v5, v5
	v_add_f32_e32 v6, 1.0, v6
	v_add_f32_e32 v7, 1.0, v7
	v_rcp_f32_e32 v6, v6
	v_rcp_f32_e32 v7, v7
	v_pk_fma_f32 v[4:5], v[4:5], 2.0, 1.0 op_sel_hi:[1,0,0] neg_lo:[1,0,0] neg_hi:[1,0,0]
	v_pk_mul_f32 v[0:1], v[0:1], 0.5 op_sel_hi:[1,0]
	v_pk_add_f32 v[4:5], v[4:5], 1.0 op_sel_hi:[1,0]
	v_pk_mul_f32 v[2:3], v[2:3], 0.5 op_sel_hi:[1,0]
	v_pk_mul_f32 v[0:1], v[0:1], v[4:5]
	v_pk_fma_f32 v[4:5], v[6:7], 2.0, 1.0 op_sel_hi:[1,0,0] neg_lo:[1,0,0] neg_hi:[1,0,0]
	v_cvt_pk_bf16_f32 v0, v0, v1
	v_pk_add_f32 v[4:5], v[4:5], 1.0 op_sel_hi:[1,0]
	s_nop 0
	v_pk_mul_f32 v[2:3], v[2:3], v[4:5]
	s_nop 0
	v_cvt_pk_bf16_f32 v1, v2, v3
	ds_write_b64 v101, v[0:1] offset:50400
